# v19align
# speedup vs baseline: 1.0004x; 1.0004x over previous
; __device__ __forceinline__ int otid() { int t = threadIdx.x; asm volatile("" : "+v"(t)); return t; }
; __device__ __forceinline__ unsigned lds_addr(LAS unsigned char* p) { return (unsigned)(size_t)p; }
; __device__ __forceinline__ int v_rd_base(int lane) { return ((lane & 3) << 3) | (((lane >> 2) & 3) << 6) | (((lane >> 4) & 1) << 5) | (((lane >> 5) & 1) << 8); }
; __device__ __forceinline__ void attn_block(const Params& p, LAS unsigned char* lds, int h, int qb) {
;     const int tid = otid(), wid = __builtin_amdgcn_readfirstlane(tid >> 6), lane = tid & 63, r32 = lane & 31, hi = lane >> 5;
;     const bf16_t* qbuf = (const bf16_t*)(p.ws + O_Q); const bf16_t* Kh = (const bf16_t*)(p.ws + O_K) + h * 192; const bf16_t* Vh = (const bf16_t*)(p.ws + O_V) + h * 128;
;     bf16_t* proj = (bf16_t*)(p.ws + O_PROJ);
;     const int qrow = qb * 256 + wid * 32 + r32;
;     bf16x8 qr[12];
;     { const bf16_t* qp = qbuf + (size_t)qrow * QW + h * 192 + hi * 8;
; #pragma unroll
;       for (int d0 = 0; d0 < 12; ++d0) qr[d0] = *(const bf16x8*)(qp + d0 * 16); }
;     const int ntiles = qb * 4 + 4, my_last = qb * 4 + (wid >> 1);
;     int ksrc[3], vsrc[2];
; #pragma unroll
;     for (int i = 0; i < 3; ++i) { const int j = i * 512 + tid, row = j / 24, cp = j % 24, c = (cp & ~7) | ((cp & 7) ^ ((row >> 1) & 7)); ksrc[i] = (row * KW + c * 8) * 2; }
; #pragma unroll
;     for (int i = 0; i < 2; ++i) { const int off = (i * 512 + tid) * 16, sub = off >> 9, rem = (off & 511) >> 1, kk = (sub >> 2) * 8 + (rem >> 5), c = (sub & 3) * 32 + (rem & 31);
;         const int k = (kk & ~0xC) | ((kk & 4) << 1) | ((kk & 8) >> 1); vsrc[i] = (k * VW + c) * 2; }
;     const int vb0 = (int)lds_addr(lds) + v_rd_base(lane);
;     const unsigned ldsw = (unsigned)wid * 1024u;
;     ...
;     float m_reg = -1e30f, l_reg = 0.f; f32x16 o[4];
; #pragma unroll
;     for (int j = 0; j < 4; ++j) o[j] = (f32x16){};
;     f32x16 pA0, pA1, pB0, pB1; float mnA, mnB, alA = 1.f, alB = 1.f; bf16x8 pa0, pa1, pa2, pa3;
;     ...
;     ADMA(0, 0, 0); __syncthreads();
;     ADMA(1, 1, 1);
;     qkt(0, pA0, pA1, lds, r32, hi, qr); partialSM(pA0, pA1, m_reg, mnA, alA);
;     __syncthreads();
.LBB0_324:
	v_mov_b32_e32 v8, v199
	s_and_b64 s[0:1], s[96:97], exec
	s_cselect_b32 s34, s16, s53
	v_readfirstlane_b32 s35, v8
	s_ashr_i32 s17, s35, 6
	s_lshl_b32 s0, s34, 8
	s_lshl_b32 s1, s17, 5
	v_and_b32_e32 v47, 31, v8
	s_add_i32 s1, s1, s0
	v_bfe_u32 v193, v8, 5, 1
	v_or_b32_e32 v180, s1, v47
	v_mov_b64_e32 v[2:3], s[44:45]
	v_mad_i64_i32 v[2:3], s[0:1], v180, s60, v[2:3]
	v_lshlrev_b32_e32 v0, 4, v193
	v_lshl_add_u64 v[2:3], v[2:3], 0, v[0:1]
	global_load_dwordx4 v[128:131], v[2:3], off
	global_load_dwordx4 v[132:135], v[2:3], off offset:32
	global_load_dwordx4 v[136:139], v[2:3], off offset:64
	global_load_dwordx4 v[140:143], v[2:3], off offset:96
	global_load_dwordx4 v[144:147], v[2:3], off offset:128
	global_load_dwordx4 v[148:151], v[2:3], off offset:160
	global_load_dwordx4 v[152:155], v[2:3], off offset:192
	global_load_dwordx4 v[156:159], v[2:3], off offset:224
	global_load_dwordx4 v[160:163], v[2:3], off offset:256
	global_load_dwordx4 v[164:167], v[2:3], off offset:288
	global_load_dwordx4 v[168:171], v[2:3], off offset:320
	global_load_dwordx4 v[172:175], v[2:3], off offset:352
	s_mov_b32 s0, 0x2aaaaaab
	v_mul_hi_i32 v0, v8, s0
	v_lshrrev_b32_e32 v2, 31, v0
	v_ashrrev_i32_e32 v0, 2, v0
	v_add_u32_e32 v0, v0, v2
	v_mul_lo_u32 v2, v0, 24
	v_sub_u32_e32 v2, v8, v2
	v_lshrrev_b32_e32 v3, 1, v0
	v_bitop3_b32 v2, v3, v2, 7 bitop3:0x6c
	v_mul_lo_u32 v0, v0, s60
	v_lshl_add_u32 v34, v2, 4, v0
	v_add_u32_e32 v0, 0x200, v8
	v_mul_hi_i32 v2, v0, s0
	v_lshrrev_b32_e32 v3, 31, v2
	v_ashrrev_i32_e32 v2, 2, v2
	v_add_u32_e32 v2, v2, v3
	v_mul_lo_u32 v3, v2, 24
	v_sub_u32_e32 v0, v0, v3
	v_lshrrev_b32_e32 v3, 1, v2
	v_bitop3_b32 v0, v3, v0, 7 bitop3:0x6c
	v_mul_lo_u32 v2, v2, s60
	v_lshl_add_u32 v36, v0, 4, v2
	v_add_u32_e32 v0, 0x400, v8
	v_mul_hi_i32 v2, v0, s0
	v_lshrrev_b32_e32 v3, 31, v2
	v_ashrrev_i32_e32 v2, 2, v2
	v_add_u32_e32 v2, v2, v3
	v_mul_lo_u32 v3, v2, 24
	v_sub_u32_e32 v0, v0, v3
	v_lshrrev_b32_e32 v3, 1, v2
	v_bitop3_b32 v0, v3, v0, 7 bitop3:0x6c
	v_lshlrev_b32_e32 v3, 4, v8
	v_mul_lo_u32 v2, v2, s60
	v_add_u32_e32 v10, 0x2000, v3
	v_lshl_add_u32 v38, v0, 4, v2
	v_lshrrev_b32_e32 v9, 1, v8
	v_bfe_i32 v2, v8, 4, 24
	v_ashrrev_i32_e32 v10, 8, v10
	v_and_b32_e32 v5, 63, v8
	v_bfe_u32 v0, v8, 2, 2
	v_and_b32_e32 v40, 8, v9
	v_lshlrev_b32_e32 v6, 1, v8
	v_and_b32_e32 v44, 0x1ffff0, v2
	v_lshrrev_b32_e32 v2, 1, v2
	v_and_b32_e32 v43, 0x1ffff0, v10
	v_lshrrev_b32_e32 v10, 1, v10
	v_or_b32_e32 v4, v40, v0
	v_and_b32_e32 v41, 0xc0, v6
	v_and_b32_e32 v42, 48, v3
	v_and_b32_e32 v46, 4, v2
	v_and_b32_e32 v45, 4, v10
	v_lshlrev_b32_e32 v5, 3, v5
	v_and_b32_e32 v3, 0xc0, v3
	s_lshl_b32 s0, s17, 10
	s_add_i32 s80, 0, 0x10000
	v_or_b32_e32 v7, v42, v41
	v_or3_b32 v2, v44, v46, v4
	v_or3_b32 v4, v43, v45, v4
	v_and_or_b32 v3, v5, 24, v3
	v_and_b32_e32 v6, 32, v6
	v_and_b32_e32 v5, 0x100, v5
	s_add_i32 s1, s80, s0
	v_ashrrev_i32_e32 v35, 31, v34
	v_lshl_or_b32 v2, v2, 11, v7
	v_lshl_or_b32 v4, v4, 11, v7
	v_or3_b32 v218, v3, v6, v5
	v_lshl_add_u64 v[6:7], s[42:43], 0, v[34:35]
	s_mov_b32 m0, s1
	v_ashrrev_i32_e32 v37, 31, v36
	global_load_lds_dwordx4 v[6:7], off
	v_lshl_add_u64 v[6:7], s[42:43], 0, v[36:37]
	s_add_i32 m0, s1, 0x2000
	v_ashrrev_i32_e32 v39, 31, v38
	global_load_lds_dwordx4 v[6:7], off
	v_lshl_add_u64 v[6:7], s[42:43], 0, v[38:39]
	s_add_i32 m0, s1, 0x4000
	s_add_i32 s17, s0, 0
	v_ashrrev_i32_e32 v3, 31, v2
	global_load_lds_dwordx4 v[6:7], off
	v_lshl_add_u64 v[6:7], s[12:13], 0, v[2:3]
	s_mov_b32 m0, s17
	v_ashrrev_i32_e32 v5, 31, v4
	global_load_lds_dwordx4 v[6:7], off
	v_lshl_add_u64 v[6:7], s[12:13], 0, v[4:5]
	s_add_i32 m0, s17, 0x2000
	s_add_i32 s49, s17, 0x16000
	global_load_lds_dwordx4 v[6:7], off
	v_lshl_add_u64 v[6:7], s[66:67], 0, v[34:35]
	s_mov_b32 m0, s49
	s_add_i32 s0, s17, 0x18000
	s_waitcnt vmcnt(0) lgkmcnt(0)
	s_barrier
	global_load_lds_dwordx4 v[6:7], off
	v_lshl_add_u64 v[6:7], s[66:67], 0, v[36:37]
	s_mov_b32 m0, s0
	s_add_i32 s1, s17, 0x1a000
	global_load_lds_dwordx4 v[6:7], off
	v_lshl_add_u64 v[6:7], s[66:67], 0, v[38:39]
	s_mov_b32 m0, s1
	v_lshl_add_u64 v[2:3], s[68:69], 0, v[2:3]
	global_load_lds_dwordx4 v[6:7], off
	s_add_i32 m0, s17, 0x4000
	s_nop 0
	global_load_lds_dwordx4 v[2:3], off
	v_lshl_add_u64 v[2:3], s[68:69], 0, v[4:5]
	s_add_i32 m0, s17, 0x6000
	v_bitop3_b32 v4, v193, v9, 7 bitop3:0x78
	global_load_lds_dwordx4 v[2:3], off
	v_bfe_u32 v3, v8, 1, 3
	v_lshlrev_b32_e32 v48, 4, v4
	v_bitop3_b32 v4, v193, v3, 2 bitop3:0x36
	v_mov_b32_e32 v2, s80
	s_movk_i32 s80, 0x180
	v_lshlrev_b32_e32 v49, 4, v4
	v_bitop3_b32 v4, v193, v3, 4 bitop3:0x36
	v_bitop3_b32 v3, v193, v3, 6 bitop3:0x36
	v_mad_u32_u24 v2, v47, s80, v2
	v_lshlrev_b32_e32 v50, 4, v4
	v_lshlrev_b32_e32 v51, 4, v3
	v_add_u32_e32 v181, v48, v2
	v_add_u32_e32 v219, v49, v2
	v_add_u32_e32 v220, v50, v2
	v_add_u32_e32 v221, v51, v2
	v_and_b32_e32 v52, 31, v199
	v_bfe_u32 v53, v199, 5, 1
	v_bfe_u32 v54, v52, 2, 1
	v_bfe_u32 v55, v52, 3, 1
	v_xor_b32_e32 v54, v54, v55
	v_mul_u32_u24_e32 v55, 12, v54
	v_xor_b32_e32 v56, v52, v55
	v_sub_u32_e32 v57, v56, v52
	v_mul_i32_i24_e32 v57, 0x180, v57
	v_bfe_u32 v54, v52, 1, 3
	v_bfe_u32 v55, v56, 1, 3
	v_or_b32_e32 v58, 0, v53
	v_xor_b32_e32 v59, v58, v55
	v_xor_b32_e32 v60, v58, v54
	v_sub_u32_e32 v59, v59, v60
	v_lshl_add_u32 v59, v59, 4, v57
	v_add_u32_e32 v181, v181, v59
	v_or_b32_e32 v58, 2, v53
	v_xor_b32_e32 v59, v58, v55
	v_xor_b32_e32 v60, v58, v54
	v_sub_u32_e32 v59, v59, v60
	v_lshl_add_u32 v59, v59, 4, v57
	v_add_u32_e32 v219, v219, v59
	v_or_b32_e32 v58, 4, v53
	v_xor_b32_e32 v59, v58, v55
	v_xor_b32_e32 v60, v58, v54
	v_sub_u32_e32 v59, v59, v60
	v_lshl_add_u32 v59, v59, 4, v57
	v_add_u32_e32 v220, v220, v59
	v_or_b32_e32 v58, 6, v53
	v_xor_b32_e32 v59, v58, v55
	v_xor_b32_e32 v60, v58, v54
	v_sub_u32_e32 v59, v59, v60
	v_lshl_add_u32 v59, v59, 4, v57
	v_add_u32_e32 v221, v221, v59
	ds_read_b128 v[2:5], v181 offset:0
	ds_read_b128 v[6:9], v181 offset:0x3000
	ds_read_b128 v[52:55], v219 offset:0
	ds_read_b128 v[56:59], v219 offset:0x3000
	s_cmp_lt_i32 s34, 0
	s_waitcnt lgkmcnt(0)
; #define LAS __attribute__((address_space(3)))
; __device__ __forceinline__ unsigned lds_addr(LAS unsigned char* p) { return (unsigned)(size_t)p; }
; #define KGRP(B_, g_) do { KRD(B_[0], kb[(2 * (g_)) & 3], ((2 * (g_)) >> 2) * 128); KRD(B_[1], kb[(2 * (g_)) & 3], ((2 * (g_)) >> 2) * 128 + 12288); \
;                           KRD(B_[2], kb[(2 * (g_) + 1) & 3], ((2 * (g_) + 1) >> 2) * 128); KRD(B_[3], kb[(2 * (g_) + 1) & 3], ((2 * (g_) + 1) >> 2) * 128 + 12288); } while (0)
; #define KWAIT(B_, n_) asm volatile("s_waitcnt lgkmcnt(" #n_ ")" : "+v"(B_[0]), "+v"(B_[1]), "+v"(B_[2]), "+v"(B_[3]) :: "memory")
; #define KWAIT(B_, n_) asm volatile("s_waitcnt lgkmcnt(" #n_ ")" : "+v"(B_[0]), "+v"(B_[1]) :: "memory")
; __device__ __forceinline__ void partialSM(f32x16& p0, f32x16& p1, float& m_reg, float& mn, float& alpha) {
;     float pmax = p0[0];
; #pragma unroll
;     for (int r = 1; r < 16; ++r) pmax = fmaxf(pmax, p0[r]);
; #pragma unroll
;     for (int r = 0; r < 16; ++r) pmax = fmaxf(pmax, p1[r]);
;     { auto rr = __builtin_amdgcn_permlane32_swap(__float_as_uint(pmax), __float_as_uint(pmax), false, false);
;       pmax = fmaxf(__uint_as_float(rr[0]), __uint_as_float(rr[1])); }
;     constexpr float C2 = 1.4426950408889634f * SCALE;
;     if (__builtin_expect(__all((pmax - m_reg) * SCALE <= THR), 1)) { mn = m_reg; alpha = 1.f; }
;     else { mn = fmaxf(m_reg, pmax); alpha = __builtin_amdgcn_exp2f((m_reg - mn) * C2); m_reg = mn; }
;     const float mnL = -mn * C2;
; #pragma unroll
;     for (int r = 0; r < 16; ++r) p0[r] = fmaf(p0[r], C2, mnL);
; #pragma unroll
;     for (int r = 0; r < 16; ++r) p1[r] = fmaf(p1[r], C2, mnL);
; #pragma unroll
;     for (int r = 0; r < 16; ++r) p0[r] = __builtin_amdgcn_exp2f(p0[r]);
; }
; __device__ __forceinline__ void qkt(int kboff, f32x16& p0, f32x16& p1, LAS unsigned char* lds, int r32, int hi, const bf16x8* qr) {
;     p0 = (f32x16){}; p1 = (f32x16){};
;     unsigned kb[4];
; #pragma unroll
;     for (int dd = 0; dd < 4; ++dd) kb[dd] = lds_addr(lds) + K_OFF + kboff + r32 * 384 + (((2 * dd + hi) ^ ((r32 >> 1) & 7)) << 4);
;     ...
;     bf16x8 bA[4];
;     KGRP(bA, 0); KWAIT(bA, 0); KMMA(bA, 0);
;     KGRP(bA, 1); KWAIT(bA, 0); KMMA(bA, 1);
;     KGRP(bA, 2); KWAIT(bA, 0); KMMA(bA, 2);
;     KGRP(bA, 3); KWAIT(bA, 0); KMMA(bA, 3);
;     KGRP(bA, 4); KWAIT(bA, 0); KMMA(bA, 4);
;     KGRP(bA, 5); KWAIT(bA, 0); KMMA(bA, 5);
;     ...
; }
	s_nop 0
	v_mfma_f32_32x32x16_bf16 v[18:33], v[2:5], v[128:131], 0
	v_mfma_f32_32x32x16_bf16 v[2:17], v[6:9], v[128:131], 0
	v_mfma_f32_32x32x16_bf16 v[18:33], v[52:55], v[132:135], v[18:33]
	ds_read_b128 v[52:55], v220 offset:0
	v_mfma_f32_32x32x16_bf16 v[2:17], v[56:59], v[132:135], v[2:17]
	ds_read_b128 v[56:59], v220 offset:0x3000
	ds_read_b128 v[60:63], v221 offset:0
	ds_read_b128 v[64:67], v221 offset:0x3000
	s_nop 0
	s_waitcnt lgkmcnt(0)
	s_nop 0
	v_mfma_f32_32x32x16_bf16 v[18:33], v[52:55], v[136:139], v[18:33]
	ds_read_b128 v[52:55], v181 offset:0x80
	v_mfma_f32_32x32x16_bf16 v[2:17], v[56:59], v[136:139], v[2:17]
	ds_read_b128 v[56:59], v181 offset:0x3080
	v_mfma_f32_32x32x16_bf16 v[18:33], v[60:63], v[140:143], v[18:33]
	ds_read_b128 v[60:63], v219 offset:0x80
	v_mfma_f32_32x32x16_bf16 v[2:17], v[64:67], v[140:143], v[2:17]
	ds_read_b128 v[64:67], v219 offset:0x3080
	s_nop 0
	s_waitcnt lgkmcnt(0)
	s_nop 0
	v_mfma_f32_32x32x16_bf16 v[18:33], v[52:55], v[144:147], v[18:33]
	ds_read_b128 v[52:55], v220 offset:0x80
	v_mfma_f32_32x32x16_bf16 v[2:17], v[56:59], v[144:147], v[2:17]
	ds_read_b128 v[56:59], v220 offset:0x3080
	v_mfma_f32_32x32x16_bf16 v[18:33], v[60:63], v[148:151], v[18:33]
	ds_read_b128 v[60:63], v221 offset:0x80
	v_mfma_f32_32x32x16_bf16 v[2:17], v[64:67], v[148:151], v[2:17]
	ds_read_b128 v[64:67], v221 offset:0x3080
	s_nop 0
	s_waitcnt lgkmcnt(0)
	s_nop 0
	v_mfma_f32_32x32x16_bf16 v[18:33], v[52:55], v[152:155], v[18:33]
	ds_read_b128 v[52:55], v181 offset:0x100
	v_mfma_f32_32x32x16_bf16 v[2:17], v[56:59], v[152:155], v[2:17]
	ds_read_b128 v[56:59], v181 offset:0x3100
	v_mfma_f32_32x32x16_bf16 v[18:33], v[60:63], v[156:159], v[18:33]
	ds_read_b128 v[60:63], v219 offset:0x100
	v_mfma_f32_32x32x16_bf16 v[2:17], v[64:67], v[156:159], v[2:17]
	ds_read_b128 v[64:67], v219 offset:0x3100
	s_nop 0
	s_waitcnt lgkmcnt(0)
	s_nop 0
	v_mfma_f32_32x32x16_bf16 v[18:33], v[52:55], v[160:163], v[18:33]
	ds_read_b128 v[52:55], v220 offset:0x100
	v_mfma_f32_32x32x16_bf16 v[2:17], v[56:59], v[160:163], v[2:17]
	ds_read_b128 v[56:59], v220 offset:0x3100
	v_mfma_f32_32x32x16_bf16 v[18:33], v[60:63], v[164:167], v[18:33]
	ds_read_b128 v[60:63], v221 offset:0x100
	v_mfma_f32_32x32x16_bf16 v[2:17], v[64:67], v[164:167], v[2:17]
	ds_read_b128 v[64:67], v221 offset:0x3100
	s_nop 0
	s_waitcnt lgkmcnt(0)
	s_waitcnt vmcnt(0) lgkmcnt(0)
	s_barrier
	v_mfma_f32_32x32x16_bf16 v[18:33], v[52:55], v[168:171], v[18:33]
	v_mfma_f32_32x32x16_bf16 v[18:33], v[60:63], v[172:175], v[18:33]
	v_mfma_f32_32x32x16_bf16 v[2:17], v[56:59], v[168:171], v[2:17]
	s_nop 10
	v_max_f32_e32 v52, v19, v19
	v_max_f32_e32 v53, v18, v18
	v_max_f32_e32 v52, v53, v52
	v_max3_f32 v52, v52, v20, v21
	v_max3_f32 v52, v52, v22, v23
	v_max3_f32 v52, v52, v24, v25
	v_max3_f32 v52, v52, v26, v27
	v_mfma_f32_32x32x16_bf16 v[2:17], v[64:67], v[172:175], v[2:17]
	v_max3_f32 v52, v52, v28, v29
	v_max3_f32 v52, v52, v30, v31
	v_max3_f32 v52, v52, v32, v33
	s_nop 8
	v_max3_f32 v52, v52, v2, v3
	v_max3_f32 v52, v52, v4, v5
	v_max3_f32 v52, v52, v6, v7
	v_max3_f32 v52, v52, v8, v9
	v_max3_f32 v52, v52, v10, v11
	v_max3_f32 v52, v52, v12, v13
	v_max3_f32 v52, v52, v14, v15
	v_max3_f32 v52, v52, v16, v17
	v_mov_b32_e32 v53, v52
	s_nop 1
	v_permlane32_swap_b32_e32 v52, v53
	v_max_f32_e32 v53, v53, v53
	v_max_f32_e32 v52, v52, v52
	v_max_f32_e32 v52, v52, v53
	v_add_f32_e32 v53, 0x7149f2ca, v52
	v_mul_f32_e32 v53, 0x3d93cd3a, v53
	v_cmp_ge_f32_e32 vcc, s63, v53
	s_cbranch_scc1 .LBB0_339
	s_lshl_b32 s34, s34, 2
	s_ashr_i32 s84, s35, 7
	s_add_i32 s80, s34, 4
	s_add_i32 s84, s84, s34
	s_cmp_eq_u64 vcc, exec
	v_max_f32_e32 v52, v52, v52
	v_max_f32_e32 v53, 0xf149f2ca, v52
	s_cselect_b64 vcc, -1, 0
	v_mov_b32_e32 v52, 0xf149f2ca
	v_cndmask_b32_e32 v244, v53, v52, vcc
	v_mul_f32_e32 v52, 0xbdd53b94, v244
	v_pk_fma_f32 v[214:215], v[2:3], s[52:53], v[52:53] op_sel_hi:[1,0,0]
	v_sub_f32_e32 v2, 0xf149f2ca, v53
	v_mul_f32_e32 v2, 0x3dd53b94, v2
	v_exp_f32_e32 v2, v2
	v_fmamk_f32 v18, v18, 0x3dd53b94, v52
	v_exp_f32_e32 v80, v18
	v_fmamk_f32 v18, v19, 0x3dd53b94, v52
	v_exp_f32_e32 v81, v18
	v_fmamk_f32 v18, v20, 0x3dd53b94, v52
	v_exp_f32_e32 v82, v18
	v_fmamk_f32 v18, v21, 0x3dd53b94, v52
	v_cndmask_b32_e64 v192, v2, 1.0, vcc
	v_add_u32_e32 v2, v44, v40
	v_exp_f32_e32 v83, v18
	v_fmamk_f32 v18, v22, 0x3dd53b94, v52
	v_add3_u32 v2, v2, v46, v0
	v_mul_u32_u24_e32 v47, 0x180, v47
	v_exp_f32_e32 v84, v18
	v_fmamk_f32 v18, v23, 0x3dd53b94, v52
	s_add_i32 s34, 0, 0x16000
	v_lshl_or_b32 v2, v2, 11, v41
	v_exp_f32_e32 v85, v18
	v_fmamk_f32 v18, v24, 0x3dd53b94, v52
	v_add_u32_e32 v3, s34, v47
	v_add_u32_e32 v2, v2, v42
	v_exp_f32_e32 v86, v18
	v_fmamk_f32 v18, v25, 0x3dd53b94, v52
	v_add_u32_e32 v226, v48, v3
	v_add_u32_e32 v227, v49, v3
	v_add_u32_e32 v228, v50, v3
	v_add_u32_e32 v229, v51, v3
	v_ashrrev_i32_e32 v3, 31, v2
	v_exp_f32_e32 v87, v18
	v_fmamk_f32 v18, v26, 0x3dd53b94, v52
	v_lshl_add_u64 v[182:183], s[50:51], 0, v[2:3]
	v_add_u32_e32 v2, v43, v40
	v_exp_f32_e32 v88, v18
	v_fmamk_f32 v18, v27, 0x3dd53b94, v52
	v_add3_u32 v0, v2, v45, v0
	v_exp_f32_e32 v89, v18
	v_fmamk_f32 v18, v28, 0x3dd53b94, v52
	v_fmamk_f32 v19, v29, 0x3dd53b94, v52
	v_fmamk_f32 v20, v30, 0x3dd53b94, v52
	v_fmamk_f32 v21, v31, 0x3dd53b94, v52
	v_fmamk_f32 v22, v32, 0x3dd53b94, v52
	v_fmamk_f32 v23, v33, 0x3dd53b94, v52
	v_lshl_or_b32 v0, v0, 11, v41
	v_exp_f32_e32 v90, v18
	v_exp_f32_e32 v91, v19
	v_add_u32_e32 v2, v0, v42
	v_exp_f32_e32 v92, v20
	v_exp_f32_e32 v93, v21
	v_exp_f32_e32 v94, v22
	v_exp_f32_e32 v95, v23
	v_pk_fma_f32 v[202:203], v[14:15], s[52:53], v[52:53] op_sel_hi:[1,0,0]
	v_ashrrev_i32_e32 v3, 31, v2
; __device__ __forceinline__ unsigned lds_addr(LAS unsigned char* p) { return (unsigned)(size_t)p; }
; __device__ __forceinline__ int v_rd_base(int lane) { return ((lane & 3) << 3) | (((lane >> 2) & 3) << 6) | (((lane >> 4) & 1) << 5) | (((lane >> 5) & 1) << 8); }
; __device__ __forceinline__ void attn_block(const Params& p, LAS unsigned char* lds, int h, int qb) {
;     ...
;     int ksrc[3], vsrc[2];
; #pragma unroll
;     for (int i = 0; i < 3; ++i) { const int j = i * 512 + tid, row = j / 24, cp = j % 24, c = (cp & ~7) | ((cp & 7) ^ ((row >> 1) & 7)); ksrc[i] = (row * KW + c * 8) * 2; }
; #pragma unroll
;     for (int i = 0; i < 2; ++i) { const int off = (i * 512 + tid) * 16, sub = off >> 9, rem = (off & 511) >> 1, kk = (sub >> 2) * 8 + (rem >> 5), c = (sub & 3) * 32 + (rem & 31);
;         const int k = (kk & ~0xC) | ((kk & 4) << 1) | ((kk & 8) >> 1); vsrc[i] = (k * VW + c) * 2; }
;     const int vb0 = (int)lds_addr(lds) + v_rd_base(lane);
;     const unsigned ldsw = (unsigned)wid * 1024u;
;     ...
;     float m_reg = -1e30f, l_reg = 0.f; f32x16 o[4];
; #pragma unroll
;     for (int j = 0; j < 4; ++j) o[j] = (f32x16){};
;     f32x16 pA0, pA1, pB0, pB1; float mnA, mnB, alA = 1.f, alB = 1.f; bf16x8 pa0, pa1, pa2, pa3;
	v_mov_b32_e32 v14, v1
	v_mov_b32_e32 v15, v1
	v_pk_fma_f32 v[200:201], v[16:17], s[52:53], v[52:53] op_sel_hi:[1,0,0]
	v_pk_fma_f32 v[204:205], v[12:13], s[52:53], v[52:53] op_sel_hi:[1,0,0]
	v_pk_fma_f32 v[206:207], v[10:11], s[52:53], v[52:53] op_sel_hi:[1,0,0]
	v_pk_fma_f32 v[208:209], v[8:9], s[52:53], v[52:53] op_sel_hi:[1,0,0]
	v_pk_fma_f32 v[210:211], v[6:7], s[52:53], v[52:53] op_sel_hi:[1,0,0]
	v_pk_fma_f32 v[212:213], v[4:5], s[52:53], v[52:53] op_sel_hi:[1,0,0]
	v_lshl_add_u64 v[184:185], s[50:51], 0, v[2:3]
	v_lshl_add_u64 v[186:187], s[40:41], 0, v[34:35]
	v_lshl_add_u64 v[188:189], s[40:41], 0, v[36:37]
	v_lshl_add_u64 v[190:191], s[40:41], 0, v[38:39]
	v_mov_b32_e32 v0, v1
	v_mov_b32_e32 v2, v1
	v_mov_b32_e32 v3, v1
	v_mov_b32_e32 v4, v1
	v_mov_b32_e32 v5, v1
	v_mov_b32_e32 v6, v1
	v_mov_b32_e32 v7, v1
	v_mov_b32_e32 v8, v1
	v_mov_b32_e32 v9, v1
	v_mov_b32_e32 v10, v1
	v_mov_b32_e32 v11, v1
	v_mov_b32_e32 v12, v1
	v_mov_b32_e32 v13, v1
	v_mov_b64_e32 v[30:31], v[14:15]
	v_mov_b64_e32 v[46:47], v[14:15]
	v_mov_b64_e32 v[62:63], v[14:15]
	v_mov_b64_e32 v[78:79], v[14:15]
	v_add_u32_e32 v225, 0, v218
	v_mov_b32_e32 v245, 0
	s_mov_b32 s86, 1
	s_mov_b32 s85, 0x10000
	v_mov_b64_e32 v[28:29], v[12:13]
	v_mov_b64_e32 v[26:27], v[10:11]
	v_mov_b64_e32 v[24:25], v[8:9]
	v_mov_b64_e32 v[22:23], v[6:7]
	v_mov_b64_e32 v[20:21], v[4:5]
	v_mov_b64_e32 v[18:19], v[2:3]
	v_mov_b64_e32 v[16:17], v[0:1]
	v_mov_b64_e32 v[44:45], v[12:13]
	v_mov_b64_e32 v[42:43], v[10:11]
	v_mov_b64_e32 v[40:41], v[8:9]
	v_mov_b64_e32 v[38:39], v[6:7]
	v_mov_b64_e32 v[36:37], v[4:5]
	v_mov_b64_e32 v[34:35], v[2:3]
	v_mov_b64_e32 v[32:33], v[0:1]
	v_mov_b64_e32 v[60:61], v[12:13]
	v_mov_b64_e32 v[58:59], v[10:11]
	v_mov_b64_e32 v[56:57], v[8:9]
	v_mov_b64_e32 v[54:55], v[6:7]
	v_mov_b64_e32 v[52:53], v[4:5]
	v_mov_b64_e32 v[50:51], v[2:3]
	v_mov_b64_e32 v[48:49], v[0:1]
	v_mov_b64_e32 v[76:77], v[12:13]
	v_mov_b64_e32 v[74:75], v[10:11]
	v_mov_b64_e32 v[72:73], v[8:9]
	v_mov_b64_e32 v[70:71], v[6:7]
	v_mov_b64_e32 v[68:69], v[4:5]
	v_mov_b64_e32 v[66:67], v[2:3]
	v_mov_b64_e32 v[64:65], v[0:1]
	s_mov_b64 s[54:55], 0x2ba60000
	s_mov_b64 s[56:57], 0x2ea40000
	v_mul_u32_u24_e32 v4, 0xaab, v199
	v_lshrrev_b32_e32 v4, 16, v4
	v_mul_u32_u24_e32 v5, 24, v4
	v_sub_u32_e32 v5, v199, v5
	v_bfe_u32 v6, v4, 1, 3
	v_and_b32_e32 v7, 7, v5
	v_xor_b32_e32 v7, v7, v6
	v_and_or_b32 v7, v5, 24, v7
	v_mul_u32_u24_e32 v4, 0xc00, v4
	v_lshl_add_u32 v8, v7, 4, v4
	v_lshl_add_u64 v[10:11], s[14:15], 0, v[186:187]
	v_lshl_add_u64 v[10:11], v[10:11], 0, s[54:55]
	v_sub_co_u32_e64 v10, s[98:99], v10, v8
	s_nop 1
	v_subbrev_co_u32_e64 v11, s[98:99], 0, v11, s[98:99]
	v_lshrrev_b32_e32 v4, 7, v199
	v_bfe_u32 v5, v199, 2, 3
	v_lshl_or_b32 v4, v4, 3, v5
	v_and_b32_e32 v5, 0xfffffff3, v4
	v_and_b32_e32 v6, 4, v4
	v_lshl_or_b32 v5, v6, 1, v5
	v_and_b32_e32 v6, 8, v4
	v_lshrrev_b32_e32 v6, 1, v6
	v_or_b32_e32 v5, v5, v6
	v_bfe_u32 v6, v199, 5, 2
	v_and_b32_e32 v7, 3, v199
	v_lshlrev_b32_e32 v6, 6, v6
	v_lshl_or_b32 v6, v7, 4, v6
	v_lshl_add_u32 v9, v5, 11, v6
	v_lshl_add_u64 v[12:13], s[14:15], 0, v[182:183]
	v_lshl_add_u64 v[12:13], v[12:13], 0, s[56:57]
	v_sub_co_u32_e64 v12, s[98:99], v12, v9
	s_nop 1
	v_subbrev_co_u32_e64 v13, s[98:99], 0, v13, s[98:99]
	s_nop 1
	v_readfirstlane_b32 s54, v10
	v_readfirstlane_b32 s55, v11
	v_readfirstlane_b32 s56, v12
	v_readfirstlane_b32 s57, v13
	v_mul_u32_u24_e32 v4, 0xaab, v199
	v_lshrrev_b32_e32 v4, 16, v4
	v_mul_u32_u24_e32 v5, 24, v4
	v_sub_u32_e32 v5, v199, v5
	v_bfe_u32 v6, v4, 1, 3
	v_and_b32_e32 v7, 7, v5
	v_xor_b32_e32 v7, v7, v6
	v_and_or_b32 v7, v5, 24, v7
	v_mul_u32_u24_e32 v4, 0xc00, v4
	v_lshl_add_u32 v186, v7, 4, v4
	v_add_u32_e32 v3, 256, v199
	v_mul_u32_u24_e32 v4, 0xaab, v3
	v_lshrrev_b32_e32 v4, 16, v4
	v_mul_u32_u24_e32 v5, 24, v4
	v_sub_u32_e32 v5, v3, v5
	v_bfe_u32 v6, v4, 1, 3
	v_and_b32_e32 v7, 7, v5
	v_xor_b32_e32 v7, v7, v6
	v_and_or_b32 v7, v5, 24, v7
	v_mul_u32_u24_e32 v4, 0xc00, v4
	v_lshl_add_u32 v187, v7, 4, v4
	v_add_u32_e32 v3, 512, v199
; __device__ __forceinline__ unsigned lds_addr(LAS unsigned char* p) { return (unsigned)(size_t)p; }
; __device__ __forceinline__ int v_rd_base(int lane) { return ((lane & 3) << 3) | (((lane >> 2) & 3) << 6) | (((lane >> 4) & 1) << 5) | (((lane >> 5) & 1) << 8); }
; __device__ __forceinline__ void qkt(int kboff, f32x16& p0, f32x16& p1, LAS unsigned char* lds, int r32, int hi, const bf16x8* qr) {
;     ...
;     for (int dd = 0; dd < 4; ++dd) kb[dd] = lds_addr(lds) + K_OFF + kboff + r32 * 384 + (((2 * dd + hi) ^ ((r32 >> 1) & 7)) << 4);
; __device__ __forceinline__ void attn_block(const Params& p, LAS unsigned char* lds, int h, int qb) {
;     ...
;     int ksrc[3], vsrc[2];
; #pragma unroll
;     for (int i = 0; i < 3; ++i) { const int j = i * 512 + tid, row = j / 24, cp = j % 24, c = (cp & ~7) | ((cp & 7) ^ ((row >> 1) & 7)); ksrc[i] = (row * KW + c * 8) * 2; }
; #pragma unroll
;     for (int i = 0; i < 2; ++i) { const int off = (i * 512 + tid) * 16, sub = off >> 9, rem = (off & 511) >> 1, kk = (sub >> 2) * 8 + (rem >> 5), c = (sub & 3) * 32 + (rem & 31);
;         const int k = (kk & ~0xC) | ((kk & 4) << 1) | ((kk & 8) >> 1); vsrc[i] = (k * VW + c) * 2; }
;     const int vb0 = (int)lds_addr(lds) + v_rd_base(lane);
;     const unsigned ldsw = (unsigned)wid * 1024u;
	v_mul_u32_u24_e32 v4, 0xaab, v3
	v_lshrrev_b32_e32 v4, 16, v4
	v_mul_u32_u24_e32 v5, 24, v4
	v_sub_u32_e32 v5, v3, v5
	v_bfe_u32 v6, v4, 1, 3
	v_and_b32_e32 v7, 7, v5
	v_xor_b32_e32 v7, v7, v6
	v_and_or_b32 v7, v5, 24, v7
	v_mul_u32_u24_e32 v4, 0xc00, v4
	v_lshl_add_u32 v188, v7, 4, v4
	v_add_u32_e32 v3, 768, v199
	v_mul_u32_u24_e32 v4, 0xaab, v3
	v_lshrrev_b32_e32 v4, 16, v4
	v_mul_u32_u24_e32 v5, 24, v4
	v_sub_u32_e32 v5, v3, v5
	v_bfe_u32 v6, v4, 1, 3
	v_and_b32_e32 v7, 7, v5
	v_xor_b32_e32 v7, v7, v6
	v_and_or_b32 v7, v5, 24, v7
	v_mul_u32_u24_e32 v4, 0xc00, v4
	v_lshl_add_u32 v189, v7, 4, v4
	v_add_u32_e32 v3, 1024, v199
	v_mul_u32_u24_e32 v4, 0xaab, v3
	v_lshrrev_b32_e32 v4, 16, v4
	v_mul_u32_u24_e32 v5, 24, v4
	v_sub_u32_e32 v5, v3, v5
	v_bfe_u32 v6, v4, 1, 3
	v_and_b32_e32 v7, 7, v5
	v_xor_b32_e32 v7, v7, v6
	v_and_or_b32 v7, v5, 24, v7
	v_mul_u32_u24_e32 v4, 0xc00, v4
	v_lshl_add_u32 v190, v7, 4, v4
	v_add_u32_e32 v3, 1280, v199
	v_mul_u32_u24_e32 v4, 0xaab, v3
	v_lshrrev_b32_e32 v4, 16, v4
	v_mul_u32_u24_e32 v5, 24, v4
	v_sub_u32_e32 v5, v3, v5
	v_bfe_u32 v6, v4, 1, 3
	v_and_b32_e32 v7, 7, v5
	v_xor_b32_e32 v7, v7, v6
	v_and_or_b32 v7, v5, 24, v7
	v_mul_u32_u24_e32 v4, 0xc00, v4
	v_lshl_add_u32 v191, v7, 4, v4
	v_lshrrev_b32_e32 v4, 7, v199
	v_bfe_u32 v5, v199, 2, 3
	v_lshl_or_b32 v4, v4, 3, v5
	v_and_b32_e32 v5, 0xfffffff3, v4
	v_and_b32_e32 v6, 4, v4
	v_lshl_or_b32 v5, v6, 1, v5
	v_and_b32_e32 v6, 8, v4
	v_lshrrev_b32_e32 v6, 1, v6
	v_or_b32_e32 v5, v5, v6
	v_bfe_u32 v6, v199, 5, 2
	v_and_b32_e32 v7, 3, v199
	v_lshlrev_b32_e32 v6, 6, v6
	v_lshl_or_b32 v6, v7, 4, v6
	v_lshl_add_u32 v182, v5, 11, v6
	v_add_u32_e32 v3, 256, v199
	v_lshrrev_b32_e32 v4, 7, v3
	v_bfe_u32 v5, v3, 2, 3
	v_lshl_or_b32 v4, v4, 3, v5
	v_and_b32_e32 v5, 0xfffffff3, v4
	v_and_b32_e32 v6, 4, v4
	v_lshl_or_b32 v5, v6, 1, v5
	v_and_b32_e32 v6, 8, v4
	v_lshrrev_b32_e32 v6, 1, v6
	v_or_b32_e32 v5, v5, v6
	v_bfe_u32 v6, v3, 5, 2
	v_and_b32_e32 v7, 3, v3
	v_lshlrev_b32_e32 v6, 6, v6
	v_lshl_or_b32 v6, v7, 4, v6
	v_lshl_add_u32 v183, v5, 11, v6
	v_add_u32_e32 v3, 512, v199
	v_lshrrev_b32_e32 v4, 7, v3
	v_bfe_u32 v5, v3, 2, 3
	v_lshl_or_b32 v4, v4, 3, v5
	v_and_b32_e32 v5, 0xfffffff3, v4
	v_and_b32_e32 v6, 4, v4
	v_lshl_or_b32 v5, v6, 1, v5
	v_and_b32_e32 v6, 8, v4
	v_lshrrev_b32_e32 v6, 1, v6
	v_or_b32_e32 v5, v5, v6
	v_bfe_u32 v6, v3, 5, 2
	v_and_b32_e32 v7, 3, v3
	v_lshlrev_b32_e32 v6, 6, v6
	v_lshl_or_b32 v6, v7, 4, v6
	v_lshl_add_u32 v184, v5, 11, v6
	v_add_u32_e32 v3, 768, v199
	v_lshrrev_b32_e32 v4, 7, v3
	v_bfe_u32 v5, v3, 2, 3
	v_lshl_or_b32 v4, v4, 3, v5
	v_and_b32_e32 v5, 0xfffffff3, v4
	v_and_b32_e32 v6, 4, v4
	v_lshl_or_b32 v5, v6, 1, v5
	v_and_b32_e32 v6, 8, v4
	v_lshrrev_b32_e32 v6, 1, v6
	v_or_b32_e32 v5, v5, v6
	v_bfe_u32 v6, v3, 5, 2
	v_and_b32_e32 v7, 3, v3
	v_lshlrev_b32_e32 v6, 6, v6
	v_lshl_or_b32 v6, v7, 4, v6
	v_lshl_add_u32 v185, v5, 11, v6
	s_nop 4
	v_and_b32_e32 v4, 31, v199
	v_bfe_u32 v5, v199, 5, 1
	v_bfe_u32 v6, v4, 2, 1
	v_bfe_u32 v7, v4, 3, 1
	v_xor_b32_e32 v6, v6, v7
	v_mul_u32_u24_e32 v7, 12, v6
	v_xor_b32_e32 v8, v4, v7
	v_sub_u32_e32 v9, v8, v4
	v_mul_i32_i24_e32 v9, 0x180, v9
	v_bfe_u32 v6, v4, 1, 3
	v_bfe_u32 v7, v8, 1, 3
	v_or_b32_e32 v10, 0, v5
	v_xor_b32_e32 v11, v10, v7
	v_xor_b32_e32 v12, v10, v6
	v_sub_u32_e32 v11, v11, v12
	v_lshl_add_u32 v11, v11, 4, v9
	v_add_u32_e32 v226, v226, v11
	v_or_b32_e32 v10, 2, v5
	v_xor_b32_e32 v11, v10, v7
	v_xor_b32_e32 v12, v10, v6
	v_sub_u32_e32 v11, v11, v12
	v_lshl_add_u32 v11, v11, 4, v9
	v_add_u32_e32 v227, v227, v11
	v_or_b32_e32 v10, 4, v5
	v_xor_b32_e32 v11, v10, v7
	v_xor_b32_e32 v12, v10, v6
	v_sub_u32_e32 v11, v11, v12
	v_lshl_add_u32 v11, v11, 4, v9
	v_add_u32_e32 v228, v228, v11
	v_or_b32_e32 v10, 6, v5
	v_xor_b32_e32 v11, v10, v7
	v_xor_b32_e32 v12, v10, v6
	v_sub_u32_e32 v11, v11, v12
	v_lshl_add_u32 v11, v11, 4, v9
	v_add_u32_e32 v229, v229, v11
	s_nop 0
	s_nop 0
	s_nop 0
	s_nop 0
	s_nop 0
	s_nop 0
	s_nop 0
	s_nop 0
	s_nop 0
	s_nop 0
	s_nop 0
	s_nop 0
	s_nop 0
